# mixa attention softmax: running max over raw scores then one scale; removed v_mul slots kept as s_nop 0 so MFMA->VALU wait states are unchanged
# baseline (speedup 1.0000x reference)
.LBB0_348:
	s_add_i32 s20, s21, 1
	s_bitcmp1_b32 s20, 0
	s_cselect_b32 s16, 0x4800, 0
	v_add_u32_e32 v66, s16, v69
	s_min_i32 s16, s21, 21
	s_lshl_b32 s22, s16, 6
	s_waitcnt vmcnt(3)
	ds_write_b128 v66, v[50:53]
	s_waitcnt vmcnt(2)
	ds_write_b128 v66, v[54:57] offset:9216
	s_waitcnt vmcnt(1)
	ds_write_b128 v66, v[58:61] offset:4608
	s_waitcnt vmcnt(0)
	ds_write_b128 v66, v[62:65] offset:13824
	v_add_lshl_u32 v66, s22, v152, 9
	s_lshl_b32 s16, s16, 7
	v_lshl_add_u64 v[58:59], v[116:117], 0, v[66:67]
	v_lshl_add_u64 v[62:63], v[118:119], 0, s[16:17]
	s_bitcmp1_b32 s21, 0
	global_load_dwordx4 v[50:53], v[58:59], off
	global_load_dwordx4 v[54:57], v[62:63], off offset:256
	v_add_co_u32_e32 v58, vcc, s19, v58
	s_cselect_b32 s16, 0x4800, 0
	s_nop 0
	v_addc_co_u32_e32 v59, vcc, 0, v59, vcc
	s_add_i32 s16, s16, 32
	v_add_co_u32_e32 v62, vcc, s96, v62
	v_add_u32_e32 v97, s16, v151
	s_nop 0
	v_addc_co_u32_e32 v63, vcc, 0, v63, vcc
	v_lshl_add_u32 v66, v68, 1, v97
	global_load_dwordx4 v[58:61], v[58:59], off
	s_cmp_lg_u32 s20, 24
	global_load_dwordx4 v[62:65], v[62:63], off offset:256
	ds_read_b128 v[158:161], v66
	ds_read_b128 v[162:165], v66 offset:64
	s_waitcnt lgkmcnt(1)
	v_mfma_f32_16x16x32_bf16 v[166:169], v[158:161], v[34:37], 0
	s_mov_b32 s21, s20
	v_mfma_f32_16x16x32_bf16 v[158:161], v[158:161], v[46:49], 0
	s_waitcnt lgkmcnt(0)
	v_mfma_f32_16x16x32_bf16 v[166:169], v[162:165], v[42:45], v[166:169]
	v_mfma_f32_16x16x32_bf16 v[158:161], v[162:165], v[38:41], v[158:161]
	ds_read_b128 v[162:165], v66 offset:2304
	ds_read_b128 v[170:173], v66 offset:2368
	s_nop 4
	s_nop 0
	s_nop 0
	s_waitcnt lgkmcnt(1)
	v_mfma_f32_16x16x32_bf16 v[174:177], v[162:165], v[34:37], 0
	v_mfma_f32_16x16x32_bf16 v[162:165], v[162:165], v[46:49], 0
	s_waitcnt lgkmcnt(0)
	v_mfma_f32_16x16x32_bf16 v[174:177], v[170:173], v[42:45], v[174:177]
	v_mfma_f32_16x16x32_bf16 v[162:165], v[170:173], v[38:41], v[162:165]
	ds_read_b128 v[170:173], v66 offset:4608
	ds_read_b128 v[188:191], v66 offset:4672
	s_waitcnt lgkmcnt(1)
	v_mfma_f32_16x16x32_bf16 v[192:195], v[170:173], v[34:37], 0
	v_mfma_f32_16x16x32_bf16 v[170:173], v[170:173], v[46:49], 0
	s_waitcnt lgkmcnt(0)
	v_mfma_f32_16x16x32_bf16 v[192:195], v[188:191], v[42:45], v[192:195]
	v_mfma_f32_16x16x32_bf16 v[170:173], v[188:191], v[38:41], v[170:173]
	ds_read_b128 v[188:191], v66 offset:6912
	ds_read_b128 v[196:199], v66 offset:6976
	s_nop 0
	v_max3_f32 v66, v166, s97, v167
	s_waitcnt lgkmcnt(1)
	v_mfma_f32_16x16x32_bf16 v[200:203], v[188:191], v[34:37], 0
	s_nop 0
	v_max3_f32 v66, v66, v168, v169
	s_nop 0
	s_waitcnt lgkmcnt(0)
	v_mfma_f32_16x16x32_bf16 v[200:203], v[196:199], v[42:45], v[200:203]
	s_nop 0
	v_max3_f32 v66, v66, v174, v175
	s_nop 0
	s_nop 0
	v_max3_f32 v66, v66, v176, v177
	s_nop 0
	s_nop 0
	v_max3_f32 v66, v66, v192, v193
	s_nop 0
	s_nop 0
	v_max3_f32 v66, v66, v194, v195
	s_nop 0
	s_nop 0
	v_max3_f32 v66, v66, v200, v201
	s_nop 0
	s_nop 0
	v_max3_f32 v66, v66, v202, v203
	ds_bpermute_b32 v91, v89, v66
	v_mfma_f32_16x16x32_bf16 v[188:191], v[188:191], v[46:49], 0
	s_nop 0
	s_waitcnt lgkmcnt(0)
	v_max_f32_e32 v91, v91, v91
	v_max_f32_e32 v66, v66, v91
	ds_bpermute_b32 v91, v87, v66
	v_mfma_f32_16x16x32_bf16 v[188:191], v[196:199], v[38:41], v[188:191]
	s_waitcnt lgkmcnt(0)
	v_max_f32_e32 v66, v66, v91
	v_mul_f32_e32 v66, 0x3fb8aa3b, v66
	v_max_f32_e32 v66, v95, v66
	v_sub_f32_e32 v91, v95, v66
	v_exp_f32_e32 v180, v91
	v_fma_f32 v91, v166, s81, -v66
	v_exp_f32_e32 v166, v91
	v_fma_f32 v91, v167, s81, -v66
	v_exp_f32_e32 v184, v91
	v_fma_f32 v91, v168, s81, -v66
	v_exp_f32_e32 v168, v91
	v_fma_f32 v91, v169, s81, -v66
	v_exp_f32_e32 v196, v91
	v_fma_f32 v91, v174, s81, -v66
	v_exp_f32_e32 v174, v91
	v_fma_f32 v91, v175, s81, -v66
	v_exp_f32_e32 v198, v91
	v_fma_f32 v91, v176, s81, -v66
	v_exp_f32_e32 v176, v91
	v_fma_f32 v91, v177, s81, -v66
	v_exp_f32_e32 v204, v91
	v_fma_f32 v91, v192, s81, -v66
	v_exp_f32_e32 v192, v91
	v_fma_f32 v91, v193, s81, -v66
	v_exp_f32_e32 v206, v91
	v_fma_f32 v91, v194, s81, -v66
	v_exp_f32_e32 v194, v91
	v_fma_f32 v91, v195, s81, -v66
	v_exp_f32_e32 v208, v91
	v_fma_f32 v91, v200, s81, -v66
	v_exp_f32_e32 v200, v91
	v_fma_f32 v91, v201, s81, -v66
	v_exp_f32_e32 v210, v91
	v_fma_f32 v91, v202, s81, -v66
	v_exp_f32_e32 v202, v91
	v_fma_f32 v91, v203, s81, -v66
	v_exp_f32_e32 v212, v91
	s_nop 0
	s_nop 0
	v_max3_f32 v91, v158, s97, v159
	s_nop 0
	v_max3_f32 v91, v91, v160, v161
	s_nop 0
	s_nop 0
	v_max3_f32 v91, v91, v162, v163
	s_nop 0
	s_nop 0
	v_max3_f32 v91, v91, v164, v165
	s_nop 0
	s_nop 0
	v_max3_f32 v91, v91, v170, v171
	s_nop 0
	s_nop 0
	v_max3_f32 v91, v91, v172, v173
	s_nop 0
	s_nop 0
	v_max3_f32 v91, v91, v188, v189
	s_nop 0
	s_nop 0
	v_max3_f32 v91, v91, v190, v191
	ds_bpermute_b32 v95, v89, v91
	s_waitcnt lgkmcnt(0)
	v_max_f32_e32 v95, v95, v95
	v_max_f32_e32 v91, v91, v95
	ds_bpermute_b32 v95, v87, v91
	s_waitcnt lgkmcnt(0)
	v_max_f32_e32 v91, v91, v95
	v_mul_f32_e32 v91, 0x3fb8aa3b, v91
	v_max_f32_e32 v91, v93, v91
	v_sub_f32_e32 v93, v93, v91
	v_exp_f32_e32 v181, v93
	v_fma_f32 v93, v158, s81, -v91
	v_exp_f32_e32 v167, v93
	v_fma_f32 v93, v159, s81, -v91
	v_exp_f32_e32 v185, v93
	v_fma_f32 v93, v160, s81, -v91
	v_exp_f32_e32 v169, v93
	v_fma_f32 v93, v161, s81, -v91
	v_exp_f32_e32 v197, v93
	v_fma_f32 v93, v162, s81, -v91
	v_exp_f32_e32 v175, v93
	v_fma_f32 v93, v163, s81, -v91
	v_exp_f32_e32 v199, v93
	v_fma_f32 v93, v164, s81, -v91
	v_exp_f32_e32 v177, v93
	v_fma_f32 v93, v165, s81, -v91
	v_exp_f32_e32 v205, v93
	v_fma_f32 v93, v170, s81, -v91
	v_exp_f32_e32 v193, v93
	v_fma_f32 v93, v171, s81, -v91
	v_exp_f32_e32 v207, v93
	v_fma_f32 v93, v172, s81, -v91
	v_exp_f32_e32 v195, v93
	v_fma_f32 v93, v173, s81, -v91
	v_pk_add_f32 v[162:163], v[166:167], 0 op_sel_hi:[1,0]
	v_exp_f32_e32 v209, v93
	v_fma_f32 v93, v188, s81, -v91
	v_pk_add_f32 v[162:163], v[184:185], v[162:163]
	v_exp_f32_e32 v201, v93
	v_fma_f32 v93, v189, s81, -v91
	v_pk_add_f32 v[162:163], v[168:169], v[162:163]
	v_exp_f32_e32 v211, v93
	v_fma_f32 v93, v190, s81, -v91
	v_pk_add_f32 v[162:163], v[196:197], v[162:163]
	v_exp_f32_e32 v203, v93
	v_fma_f32 v93, v191, s81, -v91
	v_pk_add_f32 v[162:163], v[174:175], v[162:163]
	v_exp_f32_e32 v213, v93
	v_add_u32_e32 v93, v97, v68
	v_cvt_pk_bf16_f32 v158, v166, v184
	v_pk_add_f32 v[214:215], v[198:199], v[162:163]
	v_mov_b32_e32 v166, v181
	v_add_u32_e32 v95, 0x2000, v93
	v_cvt_pk_bf16_f32 v159, v168, v196
	v_cvt_pk_bf16_f32 v160, v174, v198
	v_cvt_pk_bf16_f32 v161, v176, v204
	v_pk_add_f32 v[170:171], v[176:177], v[214:215]
	v_pk_mul_f32 v[8:9], v[8:9], v[166:167] op_sel_hi:[1,0]
	v_pk_mul_f32 v[6:7], v[6:7], v[166:167] op_sel_hi:[1,0]
	v_pk_mul_f32 v[4:5], v[4:5], v[166:167] op_sel_hi:[1,0]
	v_pk_mul_f32 v[2:3], v[2:3], v[166:167] op_sel_hi:[1,0]
	v_pk_mul_f32 v[12:13], v[12:13], v[166:167] op_sel_hi:[1,0]
	v_pk_mul_f32 v[10:11], v[10:11], v[166:167] op_sel_hi:[1,0]
	v_pk_mul_f32 v[16:17], v[16:17], v[166:167] op_sel_hi:[1,0]
	v_pk_mul_f32 v[14:15], v[14:15], v[166:167] op_sel_hi:[1,0]
	v_cvt_pk_bf16_f32 v166, v167, v185
	v_cvt_pk_bf16_f32 v167, v169, v197
	v_cvt_pk_bf16_f32 v168, v175, v199
	v_cvt_pk_bf16_f32 v169, v177, v205
	ds_read2_b64 v[174:177], v95 offset0:128 offset1:132
	v_pk_mul_f32 v[28:29], v[28:29], v[180:181] op_sel_hi:[1,0]
	v_pk_mul_f32 v[26:27], v[26:27], v[180:181] op_sel_hi:[1,0]
	v_pk_add_f32 v[170:171], v[204:205], v[170:171]
	s_waitcnt lgkmcnt(0)
	v_mfma_f32_16x16x32_bf16 v[6:9], v[174:177], v[166:169], v[6:9]
	v_add_f32_e64 v170, v192, v170
	v_add_f32_e64 v171, v193, v171
	v_cvt_pk_bf16_f32 v162, v192, v206
	v_pk_add_f32 v[170:171], v[206:207], v[170:171]
	v_mfma_f32_16x16x32_bf16 v[26:29], v[174:177], v[158:161], v[26:29]
	ds_read2_b64 v[174:177], v95 offset0:136 offset1:140
	v_pk_add_f32 v[170:171], v[194:195], v[170:171]
	v_cvt_pk_bf16_f32 v163, v194, v208
	v_pk_add_f32 v[170:171], v[208:209], v[170:171]
	v_cvt_pk_bf16_f32 v164, v200, v210
	v_pk_add_f32 v[170:171], v[200:201], v[170:171]
	v_cvt_pk_bf16_f32 v165, v202, v212
	v_pk_add_f32 v[170:171], v[210:211], v[170:171]
	v_cvt_pk_bf16_f32 v172, v201, v211
	v_pk_add_f32 v[170:171], v[202:203], v[170:171]
	v_cvt_pk_bf16_f32 v173, v203, v213
	v_pk_add_f32 v[170:171], v[212:213], v[170:171]
	v_add_u32_e32 v95, 0x2800, v93
	v_pk_fma_f32 v[112:113], v[112:113], v[180:181], v[170:171]
	v_cvt_pk_bf16_f32 v170, v193, v207
	v_cvt_pk_bf16_f32 v171, v195, v209
	s_waitcnt lgkmcnt(0)
	v_mfma_f32_16x16x32_bf16 v[26:29], v[174:177], v[162:165], v[26:29]
	v_mul_f32_e64 v20, v20, v180
	v_mul_f32_e64 v21, v21, v180
	v_pk_mul_f32 v[18:19], v[18:19], v[180:181] op_sel_hi:[1,0]
	v_pk_mul_f32 v[24:25], v[24:25], v[180:181] op_sel_hi:[1,0]
	v_mfma_f32_16x16x32_bf16 v[6:9], v[174:177], v[170:173], v[6:9]
	ds_read2_b64 v[174:177], v95 offset0:160 offset1:164
	v_pk_mul_f32 v[22:23], v[22:23], v[180:181] op_sel_hi:[1,0]
	v_pk_mul_f32 v[32:33], v[32:33], v[180:181] op_sel_hi:[1,0]
	s_waitcnt lgkmcnt(0)
	v_mfma_f32_16x16x32_bf16 v[18:21], v[174:177], v[158:161], v[18:21]
	v_mul_f32_e64 v30, v30, v180
	v_mul_f32_e64 v31, v31, v180
	v_mfma_f32_16x16x32_bf16 v[2:5], v[174:177], v[166:169], v[2:5]
	ds_read2_b64 v[174:177], v95 offset0:168 offset1:172
	v_add_u32_e32 v95, 0x3000, v93
	v_add_u32_e32 v93, 0x3800, v93
	s_waitcnt lgkmcnt(0)
	v_mfma_f32_16x16x32_bf16 v[18:21], v[174:177], v[162:165], v[18:21]
	v_mfma_f32_16x16x32_bf16 v[2:5], v[174:177], v[170:173], v[2:5]
	ds_read2_b64 v[174:177], v95 offset0:192 offset1:196
	s_waitcnt lgkmcnt(0)
	v_mfma_f32_16x16x32_bf16 v[22:25], v[174:177], v[158:161], v[22:25]
	v_mfma_f32_16x16x32_bf16 v[10:13], v[174:177], v[166:169], v[10:13]
	ds_read2_b64 v[174:177], v95 offset0:200 offset1:204
	v_mov_b32_e32 v95, v66
	s_waitcnt lgkmcnt(0)
	v_mfma_f32_16x16x32_bf16 v[22:25], v[174:177], v[162:165], v[22:25]
	v_mfma_f32_16x16x32_bf16 v[10:13], v[174:177], v[170:173], v[10:13]
	ds_read2_b64 v[174:177], v93 offset0:224 offset1:228
	s_waitcnt lgkmcnt(0)
	v_mfma_f32_16x16x32_bf16 v[30:33], v[174:177], v[158:161], v[30:33]
	ds_read2_b64 v[158:161], v93 offset0:232 offset1:236
	v_mov_b32_e32 v93, v91
	s_waitcnt lgkmcnt(0)
	v_mfma_f32_16x16x32_bf16 v[14:17], v[174:177], v[166:169], v[14:17]
	s_barrier
	v_mfma_f32_16x16x32_bf16 v[30:33], v[158:161], v[162:165], v[30:33]
	v_mfma_f32_16x16x32_bf16 v[14:17], v[158:161], v[170:173], v[14:17]
	s_cbranch_scc1 .LBB0_348
	ds_bpermute_b32 v37, v89, v112
	v_or_b32_e32 v36, v114, v140
	s_lshl_b32 s16, s9, 1
	v_lshl_add_u64 v[34:35], v[84:85], 0, s[16:17]
	s_waitcnt lgkmcnt(0)
	v_add_f32_e32 v37, v112, v37
	ds_bpermute_b32 v38, v87, v37
	s_waitcnt lgkmcnt(0)
	v_add_f32_e32 v37, v37, v38
	v_div_scale_f32 v38, s[20:21], v37, v37, 1.0
	v_rcp_f32_e32 v39, v38
	s_nop 0
	v_fma_f32 v40, -v38, v39, 1.0
	v_fmac_f32_e32 v39, v40, v39
	v_div_scale_f32 v40, vcc, 1.0, v37, 1.0
	v_mul_f32_e32 v41, v40, v39
	v_fma_f32 v42, -v38, v41, v40
	v_fmac_f32_e32 v41, v42, v39
	v_fma_f32 v38, -v38, v41, v40
	v_div_fmas_f32 v38, v38, v39, v41
	v_div_fixup_f32 v38, v38, v37, 1.0
	v_ashrrev_i32_e32 v37, 31, v36
	v_lshlrev_b64 v[40:41], 11, v[36:37]
	v_pk_mul_f32 v[18:19], v[18:19], v[38:39] op_sel_hi:[1,0]
	v_pk_mul_f32 v[20:21], v[20:21], v[38:39] op_sel_hi:[1,0]
	v_lshl_add_u64 v[40:41], v[34:35], 0, v[40:41]
	v_cvt_pk_bf16_f32 v18, v18, v19
	v_cvt_pk_bf16_f32 v19, v20, v21
	global_store_dwordx2 v[40:41], v[18:19], off offset:32
	v_pk_mul_f32 v[18:19], v[22:23], v[38:39] op_sel_hi:[1,0]
	v_pk_mul_f32 v[20:21], v[24:25], v[38:39] op_sel_hi:[1,0]
	v_cvt_pk_bf16_f32 v18, v18, v19
	v_cvt_pk_bf16_f32 v19, v20, v21
	global_store_dwordx2 v[40:41], v[18:19], off offset:64
	v_pk_mul_f32 v[18:19], v[30:31], v[38:39] op_sel_hi:[1,0]
	v_pk_mul_f32 v[20:21], v[32:33], v[38:39] op_sel_hi:[1,0]
	v_cvt_pk_bf16_f32 v18, v18, v19
	v_cvt_pk_bf16_f32 v19, v20, v21
	global_store_dwordx2 v[40:41], v[18:19], off offset:96
	ds_bpermute_b32 v18, v89, v113
	v_pk_mul_f32 v[26:27], v[26:27], v[38:39] op_sel_hi:[1,0]
	v_pk_mul_f32 v[28:29], v[28:29], v[38:39] op_sel_hi:[1,0]
	v_cvt_pk_bf16_f32 v26, v26, v27
	v_cvt_pk_bf16_f32 v27, v28, v29
	s_waitcnt lgkmcnt(0)
	v_add_f32_e32 v18, v113, v18
	ds_bpermute_b32 v19, v87, v18
	global_store_dwordx2 v[40:41], v[26:27], off
	s_waitcnt lgkmcnt(0)
	v_add_f32_e32 v18, v18, v19
	v_div_scale_f32 v19, s[20:21], v18, v18, 1.0
	v_rcp_f32_e32 v20, v19
	s_nop 0
	v_fma_f32 v21, -v19, v20, 1.0
	v_fmac_f32_e32 v20, v21, v20
	v_div_scale_f32 v21, vcc, 1.0, v18, 1.0
	v_mul_f32_e32 v22, v21, v20
	v_fma_f32 v23, -v19, v22, v21
	v_fmac_f32_e32 v22, v23, v20
	v_fma_f32 v19, -v19, v22, v21
	v_div_fmas_f32 v19, v19, v20, v22
	v_or_b32_e32 v20, 16, v36
	v_div_fixup_f32 v18, v19, v18, 1.0
	v_ashrrev_i32_e32 v21, 31, v20
	v_lshlrev_b64 v[20:21], 11, v[20:21]
	v_pk_mul_f32 v[2:3], v[2:3], v[18:19] op_sel_hi:[1,0]
	v_pk_mul_f32 v[4:5], v[4:5], v[18:19] op_sel_hi:[1,0]
	v_lshl_add_u64 v[20:21], v[34:35], 0, v[20:21]
	v_cvt_pk_bf16_f32 v2, v2, v3
	v_cvt_pk_bf16_f32 v3, v4, v5
	global_store_dwordx2 v[20:21], v[2:3], off offset:32
	v_pk_mul_f32 v[2:3], v[10:11], v[18:19] op_sel_hi:[1,0]
	v_pk_mul_f32 v[4:5], v[12:13], v[18:19] op_sel_hi:[1,0]
	v_cvt_pk_bf16_f32 v2, v2, v3
	v_cvt_pk_bf16_f32 v3, v4, v5
	v_pk_mul_f32 v[6:7], v[6:7], v[18:19] op_sel_hi:[1,0]
	v_pk_mul_f32 v[8:9], v[8:9], v[18:19] op_sel_hi:[1,0]
	global_store_dwordx2 v[20:21], v[2:3], off offset:64
	v_pk_mul_f32 v[2:3], v[14:15], v[18:19] op_sel_hi:[1,0]
	v_pk_mul_f32 v[4:5], v[16:17], v[18:19] op_sel_hi:[1,0]
	v_cvt_pk_bf16_f32 v6, v6, v7
	v_cvt_pk_bf16_f32 v7, v8, v9
	v_cvt_pk_bf16_f32 v2, v2, v3
	v_cvt_pk_bf16_f32 v3, v4, v5
	global_store_dwordx2 v[20:21], v[6:7], off
	global_store_dwordx2 v[20:21], v[2:3], off offset:96
	s_branch .LBB0_313

.LBB0_1088:
	s_add_i32 s11, s12, 1
	s_bitcmp1_b32 s11, 0
	s_cselect_b32 s13, 0x4800, 0
	v_add_u32_e32 v66, s13, v69
	s_min_i32 s13, s12, 21
	s_lshl_b32 s14, s13, 6
	s_waitcnt vmcnt(3)
	ds_write_b128 v66, v[50:53]
	s_waitcnt vmcnt(2)
	ds_write_b128 v66, v[54:57] offset:9216
	s_waitcnt vmcnt(1)
	ds_write_b128 v66, v[58:61] offset:4608
	s_waitcnt vmcnt(0)
	ds_write_b128 v66, v[62:65] offset:13824
	v_add_lshl_u32 v66, s14, v153, 9
	s_lshl_b32 s96, s13, 7
	v_lshl_add_u64 v[58:59], v[116:117], 0, v[66:67]
	v_lshl_add_u64 v[62:63], v[118:119], 0, s[96:97]
	s_bitcmp1_b32 s12, 0
	global_load_dwordx4 v[50:53], v[58:59], off
	global_load_dwordx4 v[54:57], v[62:63], off offset:256
	v_add_co_u32_e32 v58, vcc, s9, v58
	s_cselect_b32 s12, 0x4800, 0
	s_nop 0
	v_addc_co_u32_e32 v59, vcc, 0, v59, vcc
	s_add_i32 s12, s12, 32
	v_add_co_u32_e32 v62, vcc, s28, v62
	v_add_u32_e32 v97, s12, v152
	s_nop 0
	v_addc_co_u32_e32 v63, vcc, 0, v63, vcc
	v_lshl_add_u32 v66, v68, 1, v97
	global_load_dwordx4 v[58:61], v[58:59], off
	s_cmp_lg_u32 s11, 24
	global_load_dwordx4 v[62:65], v[62:63], off offset:256
	ds_read_b128 v[158:161], v66
	ds_read_b128 v[162:165], v66 offset:64
	s_waitcnt lgkmcnt(1)
	v_mfma_f32_16x16x32_bf16 v[166:169], v[158:161], v[34:37], 0
	s_mov_b32 s12, s11
	v_mfma_f32_16x16x32_bf16 v[158:161], v[158:161], v[46:49], 0
	s_waitcnt lgkmcnt(0)
	v_mfma_f32_16x16x32_bf16 v[166:169], v[162:165], v[42:45], v[166:169]
	v_mfma_f32_16x16x32_bf16 v[158:161], v[162:165], v[38:41], v[158:161]
	ds_read_b128 v[162:165], v66 offset:2304
	ds_read_b128 v[170:173], v66 offset:2368
	s_nop 4
	s_nop 0
	s_nop 0
	s_waitcnt lgkmcnt(1)
	v_mfma_f32_16x16x32_bf16 v[174:177], v[162:165], v[34:37], 0
	v_mfma_f32_16x16x32_bf16 v[162:165], v[162:165], v[46:49], 0
	s_waitcnt lgkmcnt(0)
	v_mfma_f32_16x16x32_bf16 v[174:177], v[170:173], v[42:45], v[174:177]
	v_mfma_f32_16x16x32_bf16 v[162:165], v[170:173], v[38:41], v[162:165]
	ds_read_b128 v[170:173], v66 offset:4608
	ds_read_b128 v[178:181], v66 offset:4672
	s_waitcnt lgkmcnt(1)
	v_mfma_f32_16x16x32_bf16 v[182:185], v[170:173], v[34:37], 0
	v_mfma_f32_16x16x32_bf16 v[170:173], v[170:173], v[46:49], 0
	s_waitcnt lgkmcnt(0)
	v_mfma_f32_16x16x32_bf16 v[182:185], v[178:181], v[42:45], v[182:185]
	v_mfma_f32_16x16x32_bf16 v[170:173], v[178:181], v[38:41], v[170:173]
	ds_read_b128 v[178:181], v66 offset:6912
	ds_read_b128 v[186:189], v66 offset:6976
	s_nop 0
	v_max3_f32 v66, v166, s29, v167
	s_waitcnt lgkmcnt(1)
	v_mfma_f32_16x16x32_bf16 v[190:193], v[178:181], v[34:37], 0
	s_nop 0
	v_max3_f32 v66, v66, v168, v169
	s_nop 0
	s_waitcnt lgkmcnt(0)
	v_mfma_f32_16x16x32_bf16 v[190:193], v[186:189], v[42:45], v[190:193]
	s_nop 0
	v_max3_f32 v66, v66, v174, v175
	s_nop 0
	s_nop 0
	v_max3_f32 v66, v66, v176, v177
	s_nop 0
	s_nop 0
	v_max3_f32 v66, v66, v182, v183
	s_nop 0
	s_nop 0
	v_max3_f32 v66, v66, v184, v185
	s_nop 0
	s_nop 0
	v_max3_f32 v66, v66, v190, v191
	s_nop 0
	s_nop 0
	v_max3_f32 v66, v66, v192, v193
	ds_bpermute_b32 v91, v89, v66
	v_mfma_f32_16x16x32_bf16 v[178:181], v[178:181], v[46:49], 0
	s_nop 0
	s_waitcnt lgkmcnt(0)
	v_max_f32_e32 v91, v91, v91
	v_max_f32_e32 v66, v66, v91
	ds_bpermute_b32 v91, v87, v66
	v_mfma_f32_16x16x32_bf16 v[178:181], v[186:189], v[38:41], v[178:181]
	s_waitcnt lgkmcnt(0)
	v_max_f32_e32 v66, v66, v91
	v_mul_f32_e32 v66, 0x3fb8aa3b, v66
	v_max_f32_e32 v66, v95, v66
	v_sub_f32_e32 v91, v95, v66
	v_exp_f32_e32 v186, v91
	v_fma_f32 v91, v166, s27, -v66
	v_exp_f32_e32 v166, v91
	v_fma_f32 v91, v167, s27, -v66
	v_exp_f32_e32 v188, v91
	v_fma_f32 v91, v168, s27, -v66
	v_exp_f32_e32 v168, v91
	v_fma_f32 v91, v169, s27, -v66
	v_exp_f32_e32 v194, v91
	v_fma_f32 v91, v174, s27, -v66
	v_exp_f32_e32 v174, v91
	v_fma_f32 v91, v175, s27, -v66
	v_exp_f32_e32 v196, v91
	v_fma_f32 v91, v176, s27, -v66
	v_exp_f32_e32 v176, v91
	v_fma_f32 v91, v177, s27, -v66
	v_exp_f32_e32 v198, v91
	v_fma_f32 v91, v182, s27, -v66
	v_exp_f32_e32 v182, v91
	v_fma_f32 v91, v183, s27, -v66
	v_exp_f32_e32 v200, v91
	v_fma_f32 v91, v184, s27, -v66
	v_exp_f32_e32 v184, v91
	v_fma_f32 v91, v185, s27, -v66
	v_exp_f32_e32 v202, v91
	v_fma_f32 v91, v190, s27, -v66
	v_exp_f32_e32 v190, v91
	v_fma_f32 v91, v191, s27, -v66
	v_exp_f32_e32 v204, v91
	v_fma_f32 v91, v192, s27, -v66
	v_exp_f32_e32 v192, v91
	v_fma_f32 v91, v193, s27, -v66
	v_exp_f32_e32 v206, v91
	s_nop 0
	s_nop 0
	v_max3_f32 v91, v158, s29, v159
	s_nop 0
	v_max3_f32 v91, v91, v160, v161
	s_nop 0
	s_nop 0
	v_max3_f32 v91, v91, v162, v163
	s_nop 0
	s_nop 0
	v_max3_f32 v91, v91, v164, v165
	s_nop 0
	s_nop 0
	v_max3_f32 v91, v91, v170, v171
	s_nop 0
	s_nop 0
	v_max3_f32 v91, v91, v172, v173
	s_nop 0
	s_nop 0
	v_max3_f32 v91, v91, v178, v179
	s_nop 0
	s_nop 0
	v_max3_f32 v91, v91, v180, v181
	ds_bpermute_b32 v95, v89, v91
	s_waitcnt lgkmcnt(0)
	v_max_f32_e32 v95, v95, v95
	v_max_f32_e32 v91, v91, v95
	ds_bpermute_b32 v95, v87, v91
	s_waitcnt lgkmcnt(0)
	v_max_f32_e32 v91, v91, v95
	v_mul_f32_e32 v91, 0x3fb8aa3b, v91
	v_max_f32_e32 v91, v93, v91
	v_sub_f32_e32 v93, v93, v91
	v_exp_f32_e32 v187, v93
	v_fma_f32 v93, v158, s27, -v91
	v_exp_f32_e32 v167, v93
	v_fma_f32 v93, v159, s27, -v91
	v_exp_f32_e32 v189, v93
	v_fma_f32 v93, v160, s27, -v91
	v_exp_f32_e32 v169, v93
	v_fma_f32 v93, v161, s27, -v91
	v_exp_f32_e32 v195, v93
	v_fma_f32 v93, v162, s27, -v91
	v_exp_f32_e32 v175, v93
	v_fma_f32 v93, v163, s27, -v91
	v_exp_f32_e32 v197, v93
	v_fma_f32 v93, v164, s27, -v91
	v_exp_f32_e32 v177, v93
	v_fma_f32 v93, v165, s27, -v91
	v_exp_f32_e32 v199, v93
	v_fma_f32 v93, v170, s27, -v91
	v_exp_f32_e32 v183, v93
	v_fma_f32 v93, v171, s27, -v91
	v_exp_f32_e32 v201, v93
	v_fma_f32 v93, v172, s27, -v91
	v_exp_f32_e32 v185, v93
	v_fma_f32 v93, v173, s27, -v91
	v_pk_add_f32 v[162:163], v[166:167], 0 op_sel_hi:[1,0]
	v_exp_f32_e32 v203, v93
	v_fma_f32 v93, v178, s27, -v91
	v_pk_add_f32 v[162:163], v[188:189], v[162:163]
	v_exp_f32_e32 v191, v93
	v_fma_f32 v93, v179, s27, -v91
	v_pk_add_f32 v[162:163], v[168:169], v[162:163]
	v_exp_f32_e32 v205, v93
	v_fma_f32 v93, v180, s27, -v91
	v_pk_add_f32 v[162:163], v[194:195], v[162:163]
	v_exp_f32_e32 v193, v93
	v_fma_f32 v93, v181, s27, -v91
	v_pk_add_f32 v[162:163], v[174:175], v[162:163]
	v_exp_f32_e32 v207, v93
	v_add_u32_e32 v93, v97, v68
	v_cvt_pk_bf16_f32 v158, v166, v188
	v_pk_add_f32 v[208:209], v[196:197], v[162:163]
	v_mov_b32_e32 v166, v187
	v_add_u32_e32 v95, 0x2000, v93
	v_cvt_pk_bf16_f32 v159, v168, v194
	v_cvt_pk_bf16_f32 v160, v174, v196
	v_cvt_pk_bf16_f32 v161, v176, v198
	v_pk_add_f32 v[170:171], v[176:177], v[208:209]
	v_pk_mul_f32 v[8:9], v[8:9], v[166:167] op_sel_hi:[1,0]
	v_pk_mul_f32 v[6:7], v[6:7], v[166:167] op_sel_hi:[1,0]
	v_pk_mul_f32 v[4:5], v[4:5], v[166:167] op_sel_hi:[1,0]
	v_pk_mul_f32 v[2:3], v[2:3], v[166:167] op_sel_hi:[1,0]
	v_pk_mul_f32 v[12:13], v[12:13], v[166:167] op_sel_hi:[1,0]
	v_pk_mul_f32 v[10:11], v[10:11], v[166:167] op_sel_hi:[1,0]
	v_pk_mul_f32 v[16:17], v[16:17], v[166:167] op_sel_hi:[1,0]
	v_pk_mul_f32 v[14:15], v[14:15], v[166:167] op_sel_hi:[1,0]
	v_cvt_pk_bf16_f32 v166, v167, v189
	v_cvt_pk_bf16_f32 v167, v169, v195
	v_cvt_pk_bf16_f32 v168, v175, v197
	v_cvt_pk_bf16_f32 v169, v177, v199
	ds_read2_b64 v[174:177], v95 offset0:128 offset1:132
	v_pk_mul_f32 v[28:29], v[28:29], v[186:187] op_sel_hi:[1,0]
	v_pk_mul_f32 v[26:27], v[26:27], v[186:187] op_sel_hi:[1,0]
	v_pk_add_f32 v[170:171], v[198:199], v[170:171]
	s_waitcnt lgkmcnt(0)
	v_mfma_f32_16x16x32_bf16 v[6:9], v[174:177], v[166:169], v[6:9]
	v_add_f32_e64 v170, v182, v170
	v_add_f32_e64 v171, v183, v171
	v_cvt_pk_bf16_f32 v162, v182, v200
	v_pk_add_f32 v[170:171], v[200:201], v[170:171]
	v_mfma_f32_16x16x32_bf16 v[26:29], v[174:177], v[158:161], v[26:29]
	ds_read2_b64 v[174:177], v95 offset0:136 offset1:140
	v_pk_add_f32 v[170:171], v[184:185], v[170:171]
	v_cvt_pk_bf16_f32 v163, v184, v202
	v_pk_add_f32 v[170:171], v[202:203], v[170:171]
	v_cvt_pk_bf16_f32 v164, v190, v204
	v_pk_add_f32 v[170:171], v[190:191], v[170:171]
	v_cvt_pk_bf16_f32 v165, v192, v206
	v_pk_add_f32 v[170:171], v[204:205], v[170:171]
	v_cvt_pk_bf16_f32 v172, v191, v205
	v_pk_add_f32 v[170:171], v[192:193], v[170:171]
	v_cvt_pk_bf16_f32 v173, v193, v207
	v_pk_add_f32 v[170:171], v[206:207], v[170:171]
	v_add_u32_e32 v95, 0x2800, v93
	v_pk_fma_f32 v[112:113], v[112:113], v[186:187], v[170:171]
	v_cvt_pk_bf16_f32 v170, v183, v201
	v_cvt_pk_bf16_f32 v171, v185, v203
	s_waitcnt lgkmcnt(0)
	v_mfma_f32_16x16x32_bf16 v[26:29], v[174:177], v[162:165], v[26:29]
	v_mul_f32_e64 v20, v20, v186
	v_mul_f32_e64 v21, v21, v186
	v_pk_mul_f32 v[18:19], v[18:19], v[186:187] op_sel_hi:[1,0]
	v_pk_mul_f32 v[24:25], v[24:25], v[186:187] op_sel_hi:[1,0]
	v_mfma_f32_16x16x32_bf16 v[6:9], v[174:177], v[170:173], v[6:9]
	ds_read2_b64 v[174:177], v95 offset0:160 offset1:164
	v_pk_mul_f32 v[22:23], v[22:23], v[186:187] op_sel_hi:[1,0]
	v_pk_mul_f32 v[32:33], v[32:33], v[186:187] op_sel_hi:[1,0]
	s_waitcnt lgkmcnt(0)
	v_mfma_f32_16x16x32_bf16 v[18:21], v[174:177], v[158:161], v[18:21]
	v_mul_f32_e64 v30, v30, v186
	v_mul_f32_e64 v31, v31, v186
	v_mfma_f32_16x16x32_bf16 v[2:5], v[174:177], v[166:169], v[2:5]
	ds_read2_b64 v[174:177], v95 offset0:168 offset1:172
	v_add_u32_e32 v95, 0x3000, v93
	v_add_u32_e32 v93, 0x3800, v93
	s_waitcnt lgkmcnt(0)
	v_mfma_f32_16x16x32_bf16 v[18:21], v[174:177], v[162:165], v[18:21]
	v_mfma_f32_16x16x32_bf16 v[2:5], v[174:177], v[170:173], v[2:5]
	ds_read2_b64 v[174:177], v95 offset0:192 offset1:196
	s_waitcnt lgkmcnt(0)
	v_mfma_f32_16x16x32_bf16 v[22:25], v[174:177], v[158:161], v[22:25]
	v_mfma_f32_16x16x32_bf16 v[10:13], v[174:177], v[166:169], v[10:13]
	ds_read2_b64 v[174:177], v95 offset0:200 offset1:204
	v_mov_b32_e32 v95, v66
	s_waitcnt lgkmcnt(0)
	v_mfma_f32_16x16x32_bf16 v[22:25], v[174:177], v[162:165], v[22:25]
	v_mfma_f32_16x16x32_bf16 v[10:13], v[174:177], v[170:173], v[10:13]
	ds_read2_b64 v[174:177], v93 offset0:224 offset1:228
	s_waitcnt lgkmcnt(0)
	v_mfma_f32_16x16x32_bf16 v[30:33], v[174:177], v[158:161], v[30:33]
	ds_read2_b64 v[158:161], v93 offset0:232 offset1:236
	v_mov_b32_e32 v93, v91
	s_waitcnt lgkmcnt(0)
	v_mfma_f32_16x16x32_bf16 v[14:17], v[174:177], v[166:169], v[14:17]
	s_barrier
	v_mfma_f32_16x16x32_bf16 v[30:33], v[158:161], v[162:165], v[30:33]
	v_mfma_f32_16x16x32_bf16 v[14:17], v[158:161], v[170:173], v[14:17]
	s_cbranch_scc1 .LBB0_1088
	ds_bpermute_b32 v37, v89, v112
	s_lshl_b32 s96, s10, 1
	v_or_b32_e32 v36, v114, v141
	v_lshl_add_u64 v[34:35], v[84:85], 0, s[96:97]
	s_waitcnt lgkmcnt(0)
	v_add_f32_e32 v37, v112, v37
	ds_bpermute_b32 v38, v87, v37
	s_waitcnt lgkmcnt(0)
	v_add_f32_e32 v37, v37, v38
	v_div_scale_f32 v38, s[10:11], v37, v37, 1.0
	v_rcp_f32_e32 v39, v38
	s_nop 0
	v_fma_f32 v40, -v38, v39, 1.0
	v_fmac_f32_e32 v39, v40, v39
	v_div_scale_f32 v40, vcc, 1.0, v37, 1.0
	v_mul_f32_e32 v41, v40, v39
	v_fma_f32 v42, -v38, v41, v40
	v_fmac_f32_e32 v41, v42, v39
	v_fma_f32 v38, -v38, v41, v40
	v_div_fmas_f32 v38, v38, v39, v41
	v_div_fixup_f32 v38, v38, v37, 1.0
	v_ashrrev_i32_e32 v37, 31, v36
	v_lshlrev_b64 v[40:41], 11, v[36:37]
	v_pk_mul_f32 v[18:19], v[18:19], v[38:39] op_sel_hi:[1,0]
	v_pk_mul_f32 v[20:21], v[20:21], v[38:39] op_sel_hi:[1,0]
	v_lshl_add_u64 v[40:41], v[34:35], 0, v[40:41]
	v_cvt_pk_bf16_f32 v18, v18, v19
	v_cvt_pk_bf16_f32 v19, v20, v21
	global_store_dwordx2 v[40:41], v[18:19], off offset:32
	v_pk_mul_f32 v[18:19], v[22:23], v[38:39] op_sel_hi:[1,0]
	v_pk_mul_f32 v[20:21], v[24:25], v[38:39] op_sel_hi:[1,0]
	v_cvt_pk_bf16_f32 v18, v18, v19
	v_cvt_pk_bf16_f32 v19, v20, v21
	global_store_dwordx2 v[40:41], v[18:19], off offset:64
	v_pk_mul_f32 v[18:19], v[30:31], v[38:39] op_sel_hi:[1,0]
	v_pk_mul_f32 v[20:21], v[32:33], v[38:39] op_sel_hi:[1,0]
	v_cvt_pk_bf16_f32 v18, v18, v19
	v_cvt_pk_bf16_f32 v19, v20, v21
	global_store_dwordx2 v[40:41], v[18:19], off offset:96
	ds_bpermute_b32 v18, v89, v113
	v_pk_mul_f32 v[26:27], v[26:27], v[38:39] op_sel_hi:[1,0]
	v_pk_mul_f32 v[28:29], v[28:29], v[38:39] op_sel_hi:[1,0]
	v_cvt_pk_bf16_f32 v26, v26, v27
	v_cvt_pk_bf16_f32 v27, v28, v29
	s_waitcnt lgkmcnt(0)
	v_add_f32_e32 v18, v113, v18
	ds_bpermute_b32 v19, v87, v18
	global_store_dwordx2 v[40:41], v[26:27], off
	s_waitcnt lgkmcnt(0)
	v_add_f32_e32 v18, v18, v19
	v_div_scale_f32 v19, s[10:11], v18, v18, 1.0
	v_rcp_f32_e32 v20, v19
	s_nop 0
	v_fma_f32 v21, -v19, v20, 1.0
	v_fmac_f32_e32 v20, v21, v20
	v_div_scale_f32 v21, vcc, 1.0, v18, 1.0
	v_mul_f32_e32 v22, v21, v20
	v_fma_f32 v23, -v19, v22, v21
	v_fmac_f32_e32 v22, v23, v20
	v_fma_f32 v19, -v19, v22, v21
	v_div_fmas_f32 v19, v19, v20, v22
	v_or_b32_e32 v20, 16, v36
	v_div_fixup_f32 v18, v19, v18, 1.0
	v_ashrrev_i32_e32 v21, 31, v20
	v_lshlrev_b64 v[20:21], 11, v[20:21]
	v_pk_mul_f32 v[2:3], v[2:3], v[18:19] op_sel_hi:[1,0]
	v_pk_mul_f32 v[4:5], v[4:5], v[18:19] op_sel_hi:[1,0]
	v_lshl_add_u64 v[20:21], v[34:35], 0, v[20:21]
	v_cvt_pk_bf16_f32 v2, v2, v3
	v_cvt_pk_bf16_f32 v3, v4, v5
	global_store_dwordx2 v[20:21], v[2:3], off offset:32
	v_pk_mul_f32 v[2:3], v[10:11], v[18:19] op_sel_hi:[1,0]
	v_pk_mul_f32 v[4:5], v[12:13], v[18:19] op_sel_hi:[1,0]
	v_cvt_pk_bf16_f32 v2, v2, v3
	v_cvt_pk_bf16_f32 v3, v4, v5
	v_pk_mul_f32 v[6:7], v[6:7], v[18:19] op_sel_hi:[1,0]
	v_pk_mul_f32 v[8:9], v[8:9], v[18:19] op_sel_hi:[1,0]
	global_store_dwordx2 v[20:21], v[2:3], off offset:64
	v_pk_mul_f32 v[2:3], v[14:15], v[18:19] op_sel_hi:[1,0]
	v_pk_mul_f32 v[4:5], v[16:17], v[18:19] op_sel_hi:[1,0]
	v_cvt_pk_bf16_f32 v6, v6, v7
	v_cvt_pk_bf16_f32 v7, v8, v9
	v_cvt_pk_bf16_f32 v2, v2, v3
	v_cvt_pk_bf16_f32 v3, v4, v5
	global_store_dwordx2 v[20:21], v[6:7], off
	global_store_dwordx2 v[20:21], v[2:3], off offset:96
	s_branch .LBB0_1053
